# combo27: combo23 + one static s_setprio 1 for the younger wave half (waves 4-7) over the attention phase (section 7.4), reset after the phase
# baseline (speedup 1.0000x reference)
; __device__ __forceinline__ int opaque_tid() { int t = threadIdx.x; asm volatile("" : "+v"(t)); return t; }
; __device__ __forceinline__ int v_rd_base(int lane) { return ((lane & 3) << 3) | (((lane >> 2) & 3) << 6) | (((lane >> 4) & 1) << 5) | (((lane >> 5) & 1) << 8); }
; #define DMA_V(t, slot) do { const char* vt_ = Vg + (size_t)(t) * (KVBLK * DV * 2); const unsigned vd_ = lds0 + (slot) * SHM_V + wid * 2048;                                  \
;         glds16(vt_ + vgo[0], (unsigned)__builtin_amdgcn_readfirstlane(vd_)); glds16(vt_ + vgo[1], (unsigned)__builtin_amdgcn_readfirstlane(vd_ + 1024)); } while (0)
; __device__ __forceinline__ void attn_block(const BlockRef& cur, char* lds) {
;     const int tid = opaque_tid(), wid = __builtin_amdgcn_readfirstlane(tid >> 6), lane = tid & 63, r32 = lane & 31, hi = lane >> 5;
;     const int NT = cur.P0 / KVBLK + QB / KVBLK;
;     const int qlo = cur.P0 + wid * QBLK, qm = qlo + r32 - 4 * hi;
;     char* V_lds = lds; char* K_lds = lds + NSLOT * SHM_V;
;     float* ws = (float*)(lds + LDS_WS) + wid * 64; float* li_l = ws, * al_l = ws + 32;
;     float m_reg = -1e30f, l_reg = 0; f32x16 o[4] = {};
;     const unsigned lds0 = (unsigned)(uintptr_t)lds;
;     const int vb0 = (int)lds0 + v_rd_base(lane);
;     unsigned kgo[3], vgo[2];
; #pragma unroll
;     for (int i = 0; i < 3; ++i) { const int ob = (wid * 3 + i) * 1024 + lane * 16, row = ob / 384, rem = ob % 384, g = rem >> 7, cp = (rem & 127) >> 4, c = cp ^ KS3(row);
;         kgo[i] = (unsigned)(row * 384 + g * 128 + c * 16); }
; #pragma unroll
;     for (int i = 0; i < 2; ++i) { const int ob = (wid * 2 + i) * 1024 + lane * 16, st = ob >> 9, rem = ob & 511, kk = (st >> 2) * 8 + (rem >> 6), c = (st & 3) * 32 + ((rem & 63) >> 1);
;         const int k = (kk & ~0xC) | ((kk & 4) << 1) | ((kk & 8) >> 1);
;         vgo[i] = (unsigned)(k * 256 + c * 2); }
;     const char* Kg = (const char*)cur.K; const char* Vg = (const char*)cur.V;
;     ...
;     DMA_K(0, 0); DMA_V(0, 0); DMA_K(1, 1); DMA_K(2, 2); DMA_V(1, 1);
.LBB0_537:
	s_or_b64 exec, exec, s[2:3]
	s_waitcnt vmcnt(0) lgkmcnt(0)
	s_barrier
	s_setprio 0
	v_readlane_b32 s1, v255, 3
	s_add_i32 s0, s1, 0x100
	s_cmp_lt_i32 s1, 0
	s_mov_b32 s1, s0
	s_cbranch_scc0 .LBB0_535
.LBB0_538:
	s_ashr_i32 s0, s1, 4
	s_and_b32 s2, s0, -8
	v_readlane_b32 s0, v253, 6
	s_or_b32 s6, s2, s0
	s_bfe_u32 s66, s1, 0x40003
	s_ashr_i32 s7, s6, 31
	s_lshl_b64 s[4:5], s[6:7], 13
	s_lshl_b32 s8, s66, 8
	v_writelane_b32 v255, s1, 3
	s_or_b32 s0, s4, s8
	v_writelane_b32 v255, s4, 4
	s_mul_i32 s3, s5, 0x180
	s_mul_hi_u32 s1, s0, 0x180
	s_add_i32 s1, s1, s3
	s_mulk_i32 s0, 0x180
	s_add_u32 s0, s62, s0
	v_writelane_b32 v255, s5, 5
	s_addc_u32 s1, s63, s1
	s_mul_i32 s4, s6, 0x300000
	v_writelane_b32 v255, s3, 6
	s_add_u32 s76, s64, s4
	s_mov_b32 s4, s6
	s_mul_hi_i32 s3, s6, 0x300000
	v_writelane_b32 v255, s4, 7
	s_addc_u32 s77, s65, s3
	v_mov_b32_e32 v175, v190
	v_writelane_b32 v255, s5, 8
	s_lshl_b64 s[4:5], s[6:7], 21
	s_add_u32 s10, s68, s4
	s_addc_u32 s11, s69, s5
	v_readfirstlane_b32 s3, v175
	s_ashr_i32 s6, s3, 6
	s_lshr_b32 s32, s6, 2
	s_cmp_eq_u32 s32, 1
	s_cbranch_scc0 .Lprio_y
	s_setprio 1
.Lprio_y:
	v_and_b32_e32 v32, 63, v175
	v_lshlrev_b32_e32 v35, 4, v32
	s_mul_i32 s33, s6, 0xc00
	v_or_b32_e32 v0, s33, v35
	s_mov_b32 s5, 0x2aaaaaab
	s_waitcnt lgkmcnt(0)
	v_mul_hi_i32 v1, v0, s5
	v_lshrrev_b32_e32 v2, 31, v1
	v_ashrrev_i32_e32 v1, 6, v1
	v_add_u32_e32 v1, v1, v2
	v_mul_i32_i24_e32 v2, 0x180, v1
	v_lshrrev_b32_e32 v3, 2, v1
	v_sub_u32_e32 v0, v0, v2
	v_lshrrev_b32_e32 v2, 1, v1
	v_and_b32_e32 v3, 4, v3
	v_and_or_b32 v2, v2, 3, v3
	v_and_b32_e32 v3, 0xffffff80, v0
	s_movk_i32 s9, 0x180
	v_mad_i32_i24 v1, v1, s9, v3
	v_lshlrev_b32_e32 v2, 4, v2
	v_and_b32_e32 v0, 0x70, v0
	s_add_i32 s4, s33, 0x400
	v_bitop3_b32 v160, v2, v1, v0 bitop3:0xde
	v_or_b32_e32 v0, s4, v35
	v_mul_hi_i32 v1, v0, s5
	v_lshrrev_b32_e32 v2, 31, v1
	v_ashrrev_i32_e32 v1, 6, v1
	v_add_u32_e32 v1, v1, v2
	v_mul_i32_i24_e32 v2, 0x180, v1
	v_lshrrev_b32_e32 v3, 2, v1
	v_sub_u32_e32 v0, v0, v2
	v_lshrrev_b32_e32 v2, 1, v1
	v_and_b32_e32 v3, 4, v3
	v_and_or_b32 v2, v2, 3, v3
	v_and_b32_e32 v3, 0xffffff80, v0
	v_mad_i32_i24 v1, v1, s9, v3
	v_lshlrev_b32_e32 v2, 4, v2
	v_and_b32_e32 v0, 0x70, v0
	s_add_i32 s4, s33, 0x800
	v_bitop3_b32 v166, v2, v1, v0 bitop3:0xde
	v_or_b32_e32 v0, s4, v35
	v_mul_hi_i32 v1, v0, s5
	v_lshrrev_b32_e32 v2, 31, v1
	v_ashrrev_i32_e32 v1, 6, v1
	v_add_u32_e32 v1, v1, v2
	v_mul_i32_i24_e32 v2, 0x180, v1
	v_lshrrev_b32_e32 v3, 2, v1
	v_sub_u32_e32 v0, v0, v2
	v_lshrrev_b32_e32 v2, 1, v1
	v_and_b32_e32 v3, 4, v3
	v_and_or_b32 v2, v2, 3, v3
	v_and_b32_e32 v3, 0xffffff80, v0
	v_mad_i32_i24 v1, v1, s9, v3
	v_lshlrev_b32_e32 v2, 4, v2
	v_and_b32_e32 v0, 0x70, v0
	s_lshl_b32 s80, s6, 11
	s_lshl_b32 s70, s6, 5
	v_bitop3_b32 v168, v2, v1, v0 bitop3:0xde
	s_ashr_i32 s4, s80, 8
	v_lshrrev_b32_e32 v2, 1, v175
	s_add_i32 s78, s70, s8
	v_bfe_u32 v0, v175, 2, 2
	s_and_b32 s5, s4, 0xfffff0
	v_and_b32_e32 v1, 8, v2
	s_lshr_b32 s4, s4, 1
	v_lshlrev_b32_e32 v33, 3, v32
	v_or3_b32 v0, v1, v0, s5
	s_cmp_lg_u32 0, -1
	v_and_b32_e32 v34, 24, v33
	v_and_or_b32 v0, s4, 4, v0
	s_cselect_b32 s4, 0, 0
	v_writelane_b32 v255, s8, 9
	v_and_or_b32 v1, v175, 32, v34
	s_add_i32 s5, s4, 0xc000
	v_writelane_b32 v255, s6, 10
	v_lshlrev_b32_e32 v1, 1, v1
	s_add_i32 s6, s33, s5
	v_lshl_or_b32 v170, v0, 8, v1
	v_lshl_add_u64 v[0:1], s[76:77], 0, v[160:161]
	s_mov_b32 s7, m0
	s_mov_b32 m0, s6
	s_nop 0
	global_load_lds_dwordx4 v[0:1], off
	s_mov_b32 m0, s7
	v_mov_b32_e32 v167, v161
	s_add_i32 s6, s4, s33
	v_lshl_add_u64 v[0:1], s[76:77], 0, v[166:167]
	s_add_i32 s7, s6, 0xc400
	s_mov_b32 s8, m0
	s_mov_b32 m0, s7
	s_nop 0
	global_load_lds_dwordx4 v[0:1], off
	s_mov_b32 m0, s8
	v_mov_b32_e32 v169, v161
	v_lshl_add_u64 v[0:1], s[76:77], 0, v[168:169]
	s_add_i32 s7, s6, 0xc800
	s_mov_b32 s8, m0
	s_mov_b32 m0, s7
	s_nop 0
	global_load_lds_dwordx4 v[0:1], off
	s_mov_b32 m0, s8
	v_mov_b32_e32 v171, v161
	v_lshl_add_u64 v[0:1], s[10:11], 0, v[170:171]
	s_add_i32 s4, s80, s4
	s_mov_b32 s7, m0
	s_mov_b32 m0, s4
	s_nop 0
	global_load_lds_dwordx4 v[0:1], off
	s_mov_b32 m0, s7
	s_add_i32 s7, s4, 0x400
	s_add_u32 s12, s76, 0x6000
	v_lshl_add_u64 v[0:1], v[0:1], 0, s[38:39]
	s_mov_b32 s8, m0
	s_mov_b32 m0, s7
	s_nop 0
	global_load_lds_dwordx4 v[0:1], off
	s_mov_b32 m0, s8
	s_addc_u32 s13, s77, 0
	s_add_i32 s7, s6, 0x12000
	v_lshl_add_u64 v[0:1], s[12:13], 0, v[160:161]
	s_mov_b32 s8, m0
	s_mov_b32 m0, s7
	s_nop 0
	global_load_lds_dwordx4 v[0:1], off
	s_mov_b32 m0, s8
	s_add_i32 s7, s6, 0x12400
	v_lshl_add_u64 v[0:1], s[12:13], 0, v[166:167]
	s_mov_b32 s8, m0
	s_mov_b32 m0, s7
	s_nop 0
	global_load_lds_dwordx4 v[0:1], off
	s_mov_b32 m0, s8
	v_writelane_b32 v255, s12, 11
	s_add_i32 s7, s6, 0x12800
	v_and_b32_e32 v177, 31, v175
	v_writelane_b32 v255, s13, 12
	v_lshl_add_u64 v[0:1], s[12:13], 0, v[168:169]
	s_add_u32 s12, s76, 0xc000
	s_addc_u32 s13, s77, 0
	s_mov_b32 s8, m0
	s_mov_b32 m0, s7
	s_nop 0
	global_load_lds_dwordx4 v[0:1], off
	s_mov_b32 m0, s8
	v_lshl_add_u64 v[0:1], s[12:13], 0, v[160:161]
	s_add_i32 s7, s6, 0x18000
	s_mov_b32 s8, m0
	s_mov_b32 m0, s7
	s_nop 0
	global_load_lds_dwordx4 v[0:1], off
	s_mov_b32 m0, s8
	v_lshl_add_u64 v[0:1], s[12:13], 0, v[166:167]
	v_writelane_b32 v255, s12, 13
	s_add_i32 s7, s6, 0x18400
	s_mov_b32 s8, m0
	s_mov_b32 m0, s7
	s_nop 0
	global_load_lds_dwordx4 v[0:1], off
	s_mov_b32 m0, s8
	s_add_i32 s6, s6, 0x18800
	v_writelane_b32 v255, s13, 14
	v_lshl_add_u64 v[0:1], s[12:13], 0, v[168:169]
	s_mov_b32 s7, m0
	s_mov_b32 m0, s6
	s_nop 0
	global_load_lds_dwordx4 v[0:1], off
	s_mov_b32 m0, s7
	s_add_u32 s6, s10, 0x4000
	v_writelane_b32 v255, s10, 15
; #define KSWZ(row, colB) ((row) * 384 + ((colB) ^ (KS3(row) << 4)))
; #define SBAR() __builtin_amdgcn_sched_barrier(0)
; #define ISSUE(X, d0) do { KRD(X##0, ka[(d0) & 3], ((d0) >> 2) * 128); KRD(X##1, ka[(d0) & 3], ((d0) >> 2) * 128 + 32 * KPITCH); } while (0)
; #define USE(X, d0, n) do { KWAIT(n, X##0, X##1); p0 = __builtin_amdgcn_mfma_f32_32x32x16_bf16(X##0, qr[d0], p0, 0, 0, 0); p1 = __builtin_amdgcn_mfma_f32_32x32x16_bf16(X##1, qr[d0], p1, 0, 0, 0); } while (0)
; #define ISSUE(X, d0) do { KRD(X##0, ka[(d0) & 3], ((d0) >> 2) * 128); KRD(X##1, ka[(d0) & 3], ((d0) >> 2) * 128 + 32 * KPITCH); } while (0)
; #define USE(X, d0, n) do { KWAIT(n, X##0, X##1); x0 = __builtin_amdgcn_mfma_f32_32x32x16_bf16(X##0, qr[d0], x0, 0, 0, 0); x1 = __builtin_amdgcn_mfma_f32_32x32x16_bf16(X##1, qr[d0], x1, 0, 0, 0); } while (0)
; #define WAIT_BAR(N) asm volatile("s_waitcnt vmcnt(" #N ") lgkmcnt(0)\n\ts_barrier" ::: "memory")
; __device__ __forceinline__ void qkt(f32x16& p0, f32x16& p1, unsigned kslot, int r32, int hi, const bf16x8* qr) {
;     unsigned ka[4];
; #pragma unroll
;     for (int dd = 0; dd < 4; ++dd) ka[dd] = kslot + KSWZ(r32, (dd * 16 + hi * 8) * 2);
;     bf16x8 a0, a1, b0, b1, c0, c1;
;     p0 = f32x16{}; p1 = f32x16{};
;     ...
;     ISSUE(a, 0); ISSUE(b, 1); ISSUE(c, 2);
;     USE(a, 0, 4); ISSUE(a, 3); USE(b, 1, 4); ISSUE(b, 4); USE(c, 2, 4); ISSUE(c, 5);
;     USE(a, 3, 4); ISSUE(a, 6); USE(b, 4, 4); ISSUE(b, 7); USE(c, 5, 4); ISSUE(c, 8);
;     USE(a, 6, 4); ISSUE(a, 9); USE(b, 7, 4); ISSUE(b, 10); USE(c, 8, 4); ISSUE(c, 11);
;     USE(a, 9, 4); USE(b, 10, 2); USE(c, 11, 0);
; __device__ __forceinline__ void attn_block(const BlockRef& cur, char* lds) {
;     ...
;     DMA_K(0, 0); DMA_V(0, 0); DMA_K(1, 1); DMA_K(2, 2); DMA_V(1, 1);
;     bf16x8 qr[12];
; #pragma unroll
;     for (int d0 = 0; d0 < 12; ++d0) qr[d0] = load8(cur.Q + (size_t)(wid * QBLK + r32) * DQ + d0 * 16 + hi * 8);
;     WAIT_BAR(0);
;     __builtin_amdgcn_s_waitcnt(0);
; #pragma unroll
;     for (int d0 = 0; d0 < 12; ++d0) asm volatile("" : "+v"(qr[d0]));
;     ...
;     f32x16 pA0, pA1, pB0, pB1; float mnA, mnB, alA, alB; bf16x8 pa0, pa1, pa2, pa3;
;     int ks0 = 0, ks1 = 1, ks2 = 2;
;     qkt(pA0, pA1, lds0 + NSLOT * SHM_V, r32, hi, qr); SBAR();
	s_addc_u32 s7, s11, 0
	v_bfe_u32 v176, v175, 5, 1
	v_writelane_b32 v255, s11, 16
	v_writelane_b32 v255, s6, 17
	v_or_b32_e32 v3, s70, v177
	v_lshlrev_b32_e32 v8, 4, v176
	v_lshl_add_u64 v[0:1], s[6:7], 0, v[170:171]
	v_writelane_b32 v255, s7, 18
	s_add_i32 s6, s4, 0x4000
	s_mov_b32 s7, m0
	s_mov_b32 m0, s6
	s_nop 0
	global_load_lds_dwordx4 v[0:1], off
	s_mov_b32 m0, s7
	v_lshl_add_u64 v[0:1], v[0:1], 0, s[38:39]
	s_addk_i32 s4, 0x4400
	s_mov_b32 s6, m0
	s_mov_b32 m0, s4
	s_nop 0
	global_load_lds_dwordx4 v[0:1], off
	s_mov_b32 m0, s6
	v_mov_b64_e32 v[0:1], s[0:1]
	v_mad_i64_i32 v[0:1], s[0:1], v3, s9, v[0:1]
	v_mov_b32_e32 v9, v161
	v_lshl_add_u64 v[0:1], v[0:1], 0, v[8:9]
	global_load_dwordx4 v[140:143], v[0:1], off
	global_load_dwordx4 v[136:139], v[0:1], off offset:32
	global_load_dwordx4 v[132:135], v[0:1], off offset:64
	global_load_dwordx4 v[128:131], v[0:1], off offset:96
	global_load_dwordx4 v[124:127], v[0:1], off offset:128
	global_load_dwordx4 v[120:123], v[0:1], off offset:160
	global_load_dwordx4 v[116:119], v[0:1], off offset:192
	global_load_dwordx4 v[112:115], v[0:1], off offset:224
	global_load_dwordx4 v[108:111], v[0:1], off offset:256
	global_load_dwordx4 v[104:107], v[0:1], off offset:288
	global_load_dwordx4 v[100:103], v[0:1], off offset:320
	global_load_dwordx4 v[96:99], v[0:1], off offset:352
	v_lshrrev_b32_e32 v0, 2, v175
	v_and_b32_e32 v0, 4, v0
	v_and_or_b32 v0, v2, 3, v0
	v_lshlrev_b32_e32 v9, 4, v0
	v_mov_b32_e32 v0, s5
	v_mad_u32_u24 v183, v177, s9, v0
	v_xor_b32_e32 v184, v9, v8
	s_waitcnt vmcnt(0) lgkmcnt(0)
	s_barrier
	s_waitcnt vmcnt(0) expcnt(0) lgkmcnt(0)
	v_add_u32_e32 v60, v184, v183
	ds_read_b128 v[0:3], v60 offset:0
	v_bitop3_b32 v185, v8, v9, 32 bitop3:0x36
	ds_read_b128 v[4:7], v60 offset:0x3000
	v_add_u32_e32 v61, v185, v183
	ds_read_b128 v[36:39], v61 offset:0
	v_bitop3_b32 v186, v8, v9, 64 bitop3:0x36
	ds_read_b128 v[40:43], v61 offset:0x3000
	v_add_u32_e32 v62, v186, v183
	ds_read_b128 v[44:47], v62 offset:0
	ds_read_b128 v[48:51], v62 offset:0x3000
	s_waitcnt lgkmcnt(4)
	s_movk_i32 s0, 0x60
	v_mfma_f32_32x32x16_bf16 v[16:31], v[0:3], v[140:143], 0
	v_bitop3_b32 v187, v8, v9, s0 bitop3:0x36
	v_add_u32_e32 v63, v187, v183
	ds_read_b128 v[52:55], v63 offset:0
	ds_read_b128 v[56:59], v63 offset:0x3000
	s_waitcnt lgkmcnt(4)
	v_mfma_f32_32x32x16_bf16 v[0:15], v[4:7], v[140:143], 0
	v_mfma_f32_32x32x16_bf16 v[16:31], v[36:39], v[136:139], v[16:31]
	ds_read_b128 v[36:39], v60 offset:0x80
	v_mfma_f32_32x32x16_bf16 v[0:15], v[40:43], v[136:139], v[0:15]
	ds_read_b128 v[40:43], v60 offset:0x3080
	s_waitcnt lgkmcnt(4)
	s_nop 0
	v_mfma_f32_32x32x16_bf16 v[16:31], v[44:47], v[132:135], v[16:31]
	ds_read_b128 v[44:47], v61 offset:0x80
	v_mfma_f32_32x32x16_bf16 v[0:15], v[48:51], v[132:135], v[0:15]
	ds_read_b128 v[48:51], v61 offset:0x3080
	s_waitcnt lgkmcnt(4)
	s_nop 0
	v_mfma_f32_32x32x16_bf16 v[16:31], v[52:55], v[128:131], v[16:31]
	ds_read_b128 v[52:55], v62 offset:0x80
	v_mfma_f32_32x32x16_bf16 v[0:15], v[56:59], v[128:131], v[0:15]
	ds_read_b128 v[56:59], v62 offset:0x3080
	s_waitcnt lgkmcnt(4)
	s_nop 0
	v_mfma_f32_32x32x16_bf16 v[16:31], v[36:39], v[124:127], v[16:31]
	ds_read_b128 v[36:39], v63 offset:0x80
	v_mfma_f32_32x32x16_bf16 v[0:15], v[40:43], v[124:127], v[0:15]
	ds_read_b128 v[40:43], v63 offset:0x3080
	s_waitcnt lgkmcnt(4)
	s_nop 0
	v_mfma_f32_32x32x16_bf16 v[16:31], v[44:47], v[120:123], v[16:31]
	ds_read_b128 v[44:47], v60 offset:0x100
	v_mfma_f32_32x32x16_bf16 v[0:15], v[48:51], v[120:123], v[0:15]
	ds_read_b128 v[48:51], v60 offset:0x3100
	s_waitcnt lgkmcnt(4)
	s_nop 0
	v_mfma_f32_32x32x16_bf16 v[16:31], v[52:55], v[116:119], v[16:31]
	ds_read_b128 v[52:55], v61 offset:0x100
	v_mfma_f32_32x32x16_bf16 v[0:15], v[56:59], v[116:119], v[0:15]
	ds_read_b128 v[56:59], v61 offset:0x3100
	s_waitcnt lgkmcnt(4)
	s_nop 0
	v_mfma_f32_32x32x16_bf16 v[16:31], v[36:39], v[112:115], v[16:31]
	ds_read_b128 v[36:39], v62 offset:0x100
	v_mfma_f32_32x32x16_bf16 v[0:15], v[40:43], v[112:115], v[0:15]
	ds_read_b128 v[40:43], v62 offset:0x3100
	s_waitcnt lgkmcnt(4)
	s_nop 0
	v_mfma_f32_32x32x16_bf16 v[16:31], v[44:47], v[108:111], v[16:31]
	ds_read_b128 v[44:47], v63 offset:0x100
	v_mfma_f32_32x32x16_bf16 v[0:15], v[48:51], v[108:111], v[0:15]
	ds_read_b128 v[48:51], v63 offset:0x3100
	s_waitcnt lgkmcnt(4)
	s_waitcnt lgkmcnt(2)
	s_nop 0
	s_waitcnt lgkmcnt(0)
	v_mfma_f32_32x32x16_bf16 v[16:31], v[52:55], v[104:107], v[16:31]
	v_mfma_f32_32x32x16_bf16 v[0:15], v[56:59], v[104:107], v[0:15]
	v_mfma_f32_32x32x16_bf16 v[16:31], v[36:39], v[100:103], v[16:31]
	v_lshlrev_b32_e32 v36, 2, v176
	v_sub_u32_e32 v37, v177, v36
	v_add_u32_e32 v181, s78, v37
	v_mfma_f32_32x32x16_bf16 v[0:15], v[40:43], v[100:103], v[0:15]
	v_mfma_f32_32x32x16_bf16 v[16:31], v[44:47], v[96:99], v[16:31]
	v_mfma_f32_32x32x16_bf16 v[0:15], v[48:51], v[96:99], v[0:15]
	s_cmp_gt_i32 s78, 62
	s_cbranch_scc1 .LBB0_540
; __device__ __forceinline__ void mask_tile(f32x16& p0, f32x16& p1, int dq) {
;     const float NEG = -__builtin_inff();
; #pragma unroll
;     for (int r = 0; r < 16; ++r) {
;         const int c = (r & 3) + 8 * (r >> 2);
;         if (dq - c < 0) p0[r] = NEG;
;         if (dq - c - 32 < 0) p1[r] = NEG;
;     }
	v_cmp_gt_i32_e64 s[62:63], 26, v181
	v_cmp_gt_i32_e64 s[64:65], 27, v181
	v_cmp_gt_i32_e64 s[60:61], 25, v181
	s_and_b64 s[62:63], s[64:65], s[62:63]
	v_cmp_gt_i32_e64 s[58:59], 24, v181
	s_and_b64 s[60:61], s[62:63], s[60:61]
	v_cmp_gt_i32_e64 s[56:57], 19, v181
	s_and_b64 s[58:59], s[60:61], s[58:59]
	v_cmp_gt_i32_e64 s[54:55], 18, v181
	s_and_b64 s[56:57], s[58:59], s[56:57]
	v_cmp_gt_i32_e64 s[52:53], 17, v181
	s_and_b64 s[54:55], s[56:57], s[54:55]
	v_cmp_gt_i32_e64 s[50:51], 16, v181
	s_and_b64 s[52:53], s[54:55], s[52:53]
	v_cmp_gt_i32_e64 s[48:49], 11, v181
	s_and_b64 s[50:51], s[52:53], s[50:51]
	v_cmp_gt_i32_e64 s[46:47], 10, v181
	s_and_b64 s[48:49], s[50:51], s[48:49]
	v_cmp_gt_i32_e64 s[44:45], 9, v181
	s_and_b64 s[46:47], s[48:49], s[46:47]
	v_cmp_gt_i32_e64 s[42:43], 8, v181
	s_and_b64 s[44:45], s[46:47], s[44:45]
	v_cmp_gt_i32_e64 s[40:41], 3, v181
	s_and_b64 s[42:43], s[44:45], s[42:43]
	v_cmp_gt_i32_e64 s[36:37], 2, v181
	s_and_b64 s[40:41], s[42:43], s[40:41]
	v_cmp_gt_i32_e64 s[34:35], 1, v181
	s_and_b64 s[36:37], s[40:41], s[36:37]
	v_cmp_gt_i32_e64 s[30:31], 0, v181
	s_and_b64 s[34:35], s[36:37], s[34:35]
	s_and_b64 s[30:31], s[34:35], s[30:31]
	v_cmp_gt_i32_e64 s[28:29], 58, v181
	v_cndmask_b32_e64 v16, v16, v203, s[30:31]
	v_cmp_gt_i32_e64 s[30:31], 59, v181
	v_cmp_gt_i32_e64 s[26:27], 57, v181
	s_and_b64 s[28:29], s[30:31], s[28:29]
	v_cmp_gt_i32_e64 s[24:25], 56, v181
	s_and_b64 s[26:27], s[28:29], s[26:27]
	v_cmp_gt_i32_e64 s[22:23], 51, v181
	s_and_b64 s[24:25], s[26:27], s[24:25]
	v_cmp_gt_i32_e64 s[20:21], 50, v181
	s_and_b64 s[22:23], s[24:25], s[22:23]
	v_cmp_gt_i32_e64 s[18:19], 49, v181
	s_and_b64 s[20:21], s[22:23], s[20:21]
	v_cmp_gt_i32_e64 s[16:17], 48, v181
	s_and_b64 s[18:19], s[20:21], s[18:19]
	v_cmp_gt_i32_e64 s[14:15], 43, v181
	s_and_b64 s[16:17], s[18:19], s[16:17]
	v_cmp_gt_i32_e64 s[12:13], 42, v181
	s_and_b64 s[14:15], s[16:17], s[14:15]
	v_cmp_gt_i32_e64 s[10:11], 41, v181
	s_and_b64 s[12:13], s[14:15], s[12:13]
	v_cmp_gt_i32_e64 s[8:9], 40, v181
	s_and_b64 s[10:11], s[12:13], s[10:11]
	v_cmp_gt_i32_e64 s[6:7], 35, v181
	s_and_b64 s[8:9], s[10:11], s[8:9]
	v_cmp_gt_i32_e64 s[4:5], 34, v181
	s_and_b64 s[6:7], s[8:9], s[6:7]
	v_cmp_gt_i32_e64 s[0:1], 33, v181
	s_and_b64 s[4:5], s[6:7], s[4:5]
	v_cmp_gt_i32_e32 vcc, 32, v181
	s_and_b64 s[0:1], s[4:5], s[0:1]
	s_and_b64 vcc, s[0:1], vcc
	v_cndmask_b32_e64 v31, v31, v203, s[64:65]
	v_cndmask_b32_e64 v30, v30, v203, s[62:63]
	v_cndmask_b32_e64 v29, v29, v203, s[60:61]
	v_cndmask_b32_e64 v28, v28, v203, s[58:59]
	v_cndmask_b32_e64 v27, v27, v203, s[56:57]
	v_cndmask_b32_e64 v26, v26, v203, s[54:55]
	v_cndmask_b32_e64 v25, v25, v203, s[52:53]
	v_cndmask_b32_e64 v24, v24, v203, s[50:51]
	v_cndmask_b32_e64 v23, v23, v203, s[48:49]
	v_cndmask_b32_e64 v22, v22, v203, s[46:47]
	v_cndmask_b32_e64 v21, v21, v203, s[44:45]
	v_cndmask_b32_e64 v20, v20, v203, s[42:43]
	v_cndmask_b32_e64 v19, v19, v203, s[40:41]
	v_cndmask_b32_e64 v18, v18, v203, s[36:37]
	v_cndmask_b32_e64 v17, v17, v203, s[34:35]
	v_cndmask_b32_e64 v15, v15, v203, s[30:31]
	v_cndmask_b32_e64 v14, v14, v203, s[28:29]
	v_cndmask_b32_e64 v13, v13, v203, s[26:27]
	v_cndmask_b32_e64 v12, v12, v203, s[24:25]
	v_cndmask_b32_e64 v11, v11, v203, s[22:23]
	v_cndmask_b32_e64 v10, v10, v203, s[20:21]
	v_cndmask_b32_e64 v9, v9, v203, s[18:19]
	v_cndmask_b32_e64 v8, v8, v203, s[16:17]
	v_cndmask_b32_e64 v7, v7, v203, s[14:15]
	v_cndmask_b32_e64 v6, v6, v203, s[12:13]
	v_cndmask_b32_e64 v5, v5, v203, s[10:11]
	v_cndmask_b32_e64 v4, v4, v203, s[8:9]
	v_cndmask_b32_e64 v3, v3, v203, s[6:7]
	v_cndmask_b32_e64 v2, v2, v203, s[4:5]
	v_cndmask_b32_e64 v1, v1, v203, s[0:1]
	v_cndmask_b32_e32 v0, v0, v203, vcc
